# out-proj and MLP-down sweep each XCD's two row-tile groups in reverse order (most recently written half of the hidden buffer first); on top of v72
# speedup vs baseline: 1.0004x; 1.0004x over previous
; #define LAS __attribute__((address_space(3)))
; __global__ void __launch_bounds__(NTHREADS, 2) fwd_kernel(Args a) {
;     extern __shared__ __attribute__((aligned(16))) unsigned char lds_raw[];
;     LAS unsigned char* lds = (LAS unsigned char*)lds_raw;
;     cg::grid_group grid = cg::this_grid();
;     const int G = gridDim.x, wg = blockIdx.x;
;     unsigned char* ws = a.ws;
;     float* ssqA = (float*)(ws + WS_SSQ); float* ssqB = (float*)(ws + WS_SSQ1);
;     bf16_t* XB = (bf16_t*)(ws + WS_XB); bf16_t* O2 = (bf16_t*)(ws + WS_O2); bf16_t* BIG = (bf16_t*)(ws + WS_BIG);
;     const int lo = a.ph_lo, hi = a.ph_hi;
;     int pid = 0;
;     if (threadIdx.x < 16) ((LAS unsigned*)(lds + LDS_BARST))[threadIdx.x] = 0u;
;     __syncthreads();
;     if (lo > hi) grid.sync();
;     XcdBarrier bar = xcd_barrier_post((unsigned*)(ws + WS_BAR), (volatile LAS unsigned*)(lds + LDS_BARST));
.LBB0_198:
	s_add_u32 s6, s24, 0x1e200000
	s_addc_u32 s7, s25, 0
	s_add_u32 s10, s24, 0x6200000
	s_addc_u32 s11, s25, 0
	s_add_u32 s0, s24, 0xa200000
	s_addc_u32 s1, s25, 0
	s_add_u32 s14, s24, 0xe200000
	s_addc_u32 s15, s25, 0
	v_writelane_b32 v252, s0, 36
	s_add_u32 s4, s24, 0x400000
	s_addc_u32 s5, s25, 0
	v_writelane_b32 v252, s1, 37
	v_writelane_b32 v252, s4, 38
	s_add_u32 s1, s24, 0x300000
	s_mul_i32 s0, s29, s28
	v_writelane_b32 v252, s5, 39
	v_writelane_b32 v252, s1, 40
	s_addc_u32 s1, s25, 0
	s_add_u32 s4, s24, 0x1800000
	v_writelane_b32 v252, s1, 41
	s_addc_u32 s5, s25, 0
	v_writelane_b32 v252, s4, 42
	s_mul_i32 s67, s0, s33
	v_mov_b64_e32 v[2:3], 0x7ff
	v_writelane_b32 v252, s5, 43
	s_add_u32 s4, s24, 0x1e400000
	s_addc_u32 s5, s25, 0
	v_writelane_b32 v252, s4, 44
	s_ashr_i32 s29, s28, 31
	s_ashr_i32 s3, s2, 31
	v_writelane_b32 v252, s5, 45
	s_lshl_b64 s[4:5], s[28:29], 3
	s_add_u32 s52, s4, s2
	s_addc_u32 s53, s5, s3
	s_lshr_b32 s1, s3, 29
	s_add_i32 s1, s2, s1
	s_ashr_i32 s30, s1, 3
	s_and_b32 s1, s1, -8
	s_sub_i32 s31, s2, s1
	s_add_u32 s12, s24, 0x310200
	s_addc_u32 s13, s25, 0
	s_add_u32 s18, s24, 0x310400
	s_addc_u32 s19, s25, 0
	s_add_u32 s22, s24, 0x310500
	s_addc_u32 s23, s25, 0
	s_add_u32 s64, s24, 0x310600
	s_addc_u32 s65, s25, 0
	s_add_u32 s4, s24, 0x310700
	s_addc_u32 s5, s25, 0
	v_writelane_b32 v252, s4, 46
	v_mbcnt_lo_u32_b32 v0, -1, 0
	v_mov_b32_e32 v211, 0x358637bd
	v_writelane_b32 v252, s5, 47
	s_add_u32 s4, s24, 0x310800
	s_addc_u32 s5, s25, 0
	v_writelane_b32 v252, s4, 34
	v_mov_b32_e32 v175, 0
	v_mbcnt_hi_u32_b32 v213, -1, v0
	v_writelane_b32 v252, s5, 35
	s_add_u32 s4, s24, 0x310900
	s_addc_u32 s5, s25, 0
	v_writelane_b32 v252, s4, 48
	v_mov_b32_e32 v214, 0x41b17218
	v_mov_b32_e32 v215, 0xf149f2ca
	v_writelane_b32 v252, s5, 49
	s_add_u32 s4, s24, 0x310a00
	s_addc_u32 s5, s25, 0
	v_writelane_b32 v252, s4, 50
	v_mov_b32_e32 v216, 0x7149f2ca
	s_mov_b32 s35, 0x800000
	v_writelane_b32 v252, s5, 51
	s_add_u32 s4, s24, 0x310b00
	s_addc_u32 s5, s25, 0
	v_writelane_b32 v252, s4, 52
	s_mov_b32 s63, 0x10000
	s_movk_i32 s33, 0x6000
	v_writelane_b32 v252, s5, 53
	s_add_u32 s4, s24, 0x310c00
	s_addc_u32 s5, s25, 0
	v_writelane_b32 v252, s4, 54
	s_mov_b32 s92, 0xa000
	s_movk_i32 s89, 0x1800
	v_writelane_b32 v252, s5, 55
	s_add_u32 s4, s24, 0x310d00
	s_addc_u32 s5, s25, 0
	v_writelane_b32 v252, s4, 56
	s_mov_b32 s93, 0x8800
	s_mov_b32 s90, 0xf149f2ca
	v_writelane_b32 v252, s5, 57
	s_add_u32 s4, s24, 0x310e00
	s_addc_u32 s5, s25, 0
	v_writelane_b32 v252, s4, 58
	s_mov_b32 s91, 0x42a00000
	s_mov_b64 s[94:95], 0x1000
	v_writelane_b32 v252, s5, 59
	s_add_u32 s4, s24, 0x310f00
	s_addc_u32 s5, s25, 0
	v_writelane_b32 v252, s4, 60
	s_mov_b32 s34, 0x3e800000
	s_nop 0
	v_writelane_b32 v252, s5, 61
	s_add_u32 s4, s24, 0x311000
	s_addc_u32 s5, s25, 0
	v_writelane_b32 v252, s4, 62
	s_nop 1
	v_writelane_b32 v252, s5, 63
	s_add_u32 s4, s24, 0x311100
	s_addc_u32 s5, s25, 0
	v_writelane_b32 v253, s4, 0
	v_readlane_b32 s36, v252, 16
	v_readlane_b32 s48, v252, 28
	v_writelane_b32 v253, s5, 1
	s_add_u32 s4, s24, 0x311200
	s_addc_u32 s5, s25, 0
	v_writelane_b32 v253, s4, 2
	v_readlane_b32 s49, v252, 29
	v_readlane_b32 s46, v252, 26
	v_writelane_b32 v253, s5, 3
	s_add_u32 s4, s24, 0x311300
	s_addc_u32 s5, s25, 0
	v_writelane_b32 v253, s4, 4
	s_cmp_eq_u32 s68, 15
	v_readlane_b32 s47, v252, 27
	v_writelane_b32 v253, s5, 5
	s_cselect_b64 s[4:5], -1, 0
	v_writelane_b32 v253, s4, 6
	s_cmp_eq_u32 s68, 14
	v_readlane_b32 s37, v252, 17
	v_writelane_b32 v253, s5, 7
	s_cselect_b64 s[4:5], -1, 0
	v_writelane_b32 v253, s4, 8
	s_cmp_eq_u32 s68, 13
	s_mov_b32 s36, 0x7f800000
	v_writelane_b32 v253, s5, 9
	s_cselect_b64 s[4:5], -1, 0
	v_writelane_b32 v253, s4, 10
	s_cmp_eq_u32 s68, 12
	s_mov_b32 s37, 0xffff0000
	v_writelane_b32 v253, s5, 11
	s_cselect_b64 s[4:5], -1, 0
	v_writelane_b32 v253, s4, 12
	s_cmp_eq_u32 s68, 11
	v_readlane_b32 s38, v252, 18
	v_writelane_b32 v253, s5, 13
	s_cselect_b64 s[4:5], -1, 0
	v_writelane_b32 v253, s4, 14
	s_cmp_eq_u32 s68, 10
	v_readlane_b32 s39, v252, 19
	v_writelane_b32 v253, s5, 15
	s_cselect_b64 s[4:5], -1, 0
	v_writelane_b32 v253, s4, 16
	s_cmp_eq_u32 s68, 9
	v_readlane_b32 s40, v252, 20
	v_writelane_b32 v253, s5, 17
	s_cselect_b64 s[4:5], -1, 0
	v_writelane_b32 v253, s4, 18
	s_cmp_eq_u32 s68, 8
	v_readlane_b32 s41, v252, 21
	v_writelane_b32 v253, s5, 19
	s_cselect_b64 s[4:5], -1, 0
	v_writelane_b32 v253, s4, 20
	s_cmp_eq_u32 s68, 7
	v_readlane_b32 s42, v252, 22
	v_writelane_b32 v253, s5, 21
	s_cselect_b64 s[4:5], -1, 0
	v_writelane_b32 v253, s4, 22
	s_cmp_eq_u32 s68, 6
	v_readlane_b32 s43, v252, 23
	v_writelane_b32 v253, s5, 23
	s_cselect_b64 s[4:5], -1, 0
	v_writelane_b32 v253, s4, 24
	s_cmp_eq_u32 s68, 5
	v_readlane_b32 s44, v252, 24
	v_writelane_b32 v253, s5, 25
	s_cselect_b64 s[4:5], -1, 0
	v_writelane_b32 v253, s4, 26
	s_cmp_eq_u32 s68, 4
	v_readlane_b32 s45, v252, 25
	v_writelane_b32 v253, s5, 27
	s_cselect_b64 s[4:5], -1, 0
	v_writelane_b32 v253, s4, 28
	s_cmp_eq_u32 s68, 3
	v_readlane_b32 s50, v252, 30
	v_writelane_b32 v253, s5, 29
	s_cselect_b64 s[4:5], -1, 0
	v_writelane_b32 v253, s4, 30
	s_cmp_eq_u32 s68, 2
	v_readlane_b32 s51, v252, 31
	v_writelane_b32 v253, s5, 31
	s_cselect_b64 s[4:5], -1, 0
	v_writelane_b32 v253, s4, 32
	s_cmp_eq_u32 s68, 1
	s_nop 0
	v_writelane_b32 v253, s5, 33
	s_cselect_b64 s[4:5], -1, 0
	v_writelane_b32 v253, s4, 34
	s_cmp_eq_u32 s68, 0
	s_nop 0
	v_writelane_b32 v253, s5, 35
	s_cselect_b64 s[4:5], -1, 0
	s_lshl_b32 s1, s68, 8
	v_writelane_b32 v253, s4, 36
	s_add_u32 s1, s86, s1
	v_readlane_b32 s68, v252, 0
	v_writelane_b32 v253, s5, 37
	s_addc_u32 s4, s87, 0
	s_add_u32 s8, s1, 0x1400
; #define LAS __attribute__((address_space(3)))
; __global__ void __launch_bounds__(NTHREADS, 2) fwd_kernel(Args a) {
;     ...
;     const int G = gridDim.x, wg = blockIdx.x;
;     unsigned char* ws = a.ws;
;     float* ssqA = (float*)(ws + WS_SSQ); float* ssqB = (float*)(ws + WS_SSQ1);
;     bf16_t* XB = (bf16_t*)(ws + WS_XB); bf16_t* O2 = (bf16_t*)(ws + WS_O2); bf16_t* BIG = (bf16_t*)(ws + WS_BIG);
;     const int lo = a.ph_lo, hi = a.ph_hi;
;     int pid = 0;
;     if (threadIdx.x < 16) ((LAS unsigned*)(lds + LDS_BARST))[threadIdx.x] = 0u;
;     __syncthreads();
;     if (lo > hi) grid.sync();
;     XcdBarrier bar = xcd_barrier_post((unsigned*)(ws + WS_BAR), (volatile LAS unsigned*)(lds + LDS_BARST));
;     ...
;             if (mixer == 0) { g = pg8::Gemm{XB, (const bf16_t*)(ws + WS_AWIN) + (size_t)j * 4096 * DM, MT, 4096, DM, 0}; E = pg8::EpiAct{BIG, 4096, ssqA, 0, (const float*)(ws + WS_LB) + j * 1024, 1.f, nullptr, 0}; }
;             else { g = pg8::Gemm{XB, (const bf16_t*)(ws + WS_BQKV), MT, 3072, DM, 0}; E = pg8::EpiAct{BIG, 3072, ssqA, 1, nullptr, 0.08838834764831845f * 1.4426950408889634f, (float*)(ws + WS_KMEAN), 0}; }
;             pg8::StaticOrder S; S.init(g.M, g.N, G, wg);
;             E.use_tab = build_rstd_table(lds, S, E.ssq) ? 1 : 0;
;             for (int rep = 0; rep < REP_G1; ++rep) pg8::gemm_phase<pg8::EpiAct, pg8::StaticOrder, true, true>(lds, g, S, E);
;             PH_END
;         } else {
;             PH_BEGIN for (int rep = 0; rep < REP_POOL; ++rep) pool_phase(lds, XB, ssqA, a.in[1] + i * DM, O2, G, wg); PH_END
;         }
;         if (mixer == 0) {
;             PH_BEGIN
; if ((i == 0 || i == 3) && G >= 256 && wg >= 128) { for (int rep = 0; rep < REP_CONV; ++rep) p0_phase(a, lds, G - 128, wg - 128, i == 0 ? 1 : 2, true); }
;             else for (int rep = 0; rep < REP_GLA; ++rep) gla_phase(lds, BIG, a.in[6] + j * 128, O2, G, wg);
;  PH_END
;         } else if (mixer == 1) {
;             PH_BEGIN
; for (int rep = 0; rep < REP_ATTN; ++rep) attn_phase(lds, BIG, (const float*)(ws + WS_KMEAN), (const float*)(ws + WS_BIAST), O2, G, wg);
;  PH_END
;         }
;         {
;             PH_BEGIN
;             pg8::Gemm g;
;             if (mixer == 0) g = pg8::Gemm{O2, (const bf16_t*)(ws + WS_AWOUT) + (size_t)j * DM * DM, MT, DM, DM, 0};
;             else if (mixer == 1) g = pg8::Gemm{O2, (const bf16_t*)(ws + WS_BOUT), MT, DM, DM, 0};
	s_addc_u32 s9, s4, 0
	v_writelane_b32 v253, s8, 38
	v_readlane_b32 s72, v252, 4
	v_readlane_b32 s73, v252, 5
	v_writelane_b32 v253, s9, 39
	s_add_u32 s8, s1, 0x2400
	s_addc_u32 s9, s4, 0
	s_add_u32 s4, s24, 0x313400
	s_addc_u32 s5, s25, 0
	v_writelane_b32 v253, s8, 40
	s_add_u32 s16, s24, 0x313500
	s_addc_u32 s17, s25, 0
	v_writelane_b32 v253, s9, 41
	v_writelane_b32 v253, s4, 42
	s_cmpk_lt_i32 s2, 0x200
	v_readlane_b32 s70, v252, 2
	v_writelane_b32 v253, s5, 43
	s_cselect_b64 s[4:5], -1, 0
	s_add_u32 s20, s24, 0x2c0000
	s_addc_u32 s21, s25, 0
	v_writelane_b32 v253, s4, 44
	s_cmpk_lt_i32 s2, 0x400
	v_readlane_b32 s71, v252, 3
	v_writelane_b32 v253, s5, 45
	s_cselect_b64 s[4:5], -1, 0
	v_writelane_b32 v253, s4, 46
	s_cmpk_gt_i32 s28, 0xff
	v_readlane_b32 s82, v252, 14
	v_writelane_b32 v253, s5, 47
	s_cselect_b64 s[4:5], -1, 0
	s_cmpk_gt_i32 s2, 0x7f
	s_cselect_b64 s[8:9], -1, 0
	s_and_b64 s[4:5], s[4:5], s[8:9]
	v_writelane_b32 v253, s4, 48
	s_cmpk_lt_i32 s2, 0x80
	v_readlane_b32 s83, v252, 15
	v_writelane_b32 v253, s5, 49
	s_cselect_b64 s[4:5], -1, 0
	v_writelane_b32 v253, s4, 50
	s_add_i32 s1, s88, 0xfffffc00
	v_readlane_b32 s69, v252, 1
	v_writelane_b32 v253, s5, 51
	v_writelane_b32 v253, s1, 52
	s_mov_b32 s4, s84
	v_writelane_b32 v253, s4, 53
	s_add_i32 s1, s84, 0xfffffc00
	s_mov_b64 s[68:69], s[16:17]
	v_writelane_b32 v253, s5, 54
	s_add_u32 s4, s24, 0x5900000
	v_writelane_b32 v253, s1, 55
	s_addc_u32 s5, s25, 0
	v_writelane_b32 v253, s4, 56
	s_mov_b64 s[84:85], s[12:13]
	v_readlane_b32 s78, v252, 10
	v_writelane_b32 v253, s5, 57
	s_add_u32 s4, s24, 0x3900000
	s_addc_u32 s5, s25, 0
	v_writelane_b32 v253, s4, 58
	v_readlane_b32 s79, v252, 11
	v_writelane_b32 v255, s68, 0
	v_writelane_b32 v253, s5, 59
	s_add_u32 s4, s72, 0x3000
	s_addc_u32 s5, s73, 0
	v_writelane_b32 v253, s4, 60
	s_mov_b64 s[78:79], s[18:19]
	v_writelane_b32 v255, s69, 1
	v_writelane_b32 v253, s5, 61
	s_add_u32 s4, s24, 0x1600000
	s_addc_u32 s5, s25, 0
	v_writelane_b32 v253, s4, 62
	v_readlane_b32 s80, v252, 12
	v_readlane_b32 s81, v252, 13
	v_writelane_b32 v253, s5, 63
	s_add_u32 s4, s24, 0x4100000
	s_addc_u32 s5, s25, 0
	v_writelane_b32 v254, s4, 0
	v_writelane_b32 v255, s78, 2
	s_mov_b64 s[80:81], s[22:23]
	v_writelane_b32 v254, s5, 1
	s_add_u32 s4, s24, 0x2100000
	s_addc_u32 s5, s25, 0
	v_writelane_b32 v254, s4, 2
	s_cmp_lg_u64 s[72:73], 0
	v_writelane_b32 v255, s79, 3
	v_writelane_b32 v254, s5, 3
	s_cselect_b64 s[4:5], -1, 0
	v_writelane_b32 v254, s4, 4
	v_writelane_b32 v255, s80, 4
	v_readlane_b32 s74, v252, 6
	v_writelane_b32 v254, s5, 5
	s_add_u32 s4, s24, 0x2000000
	s_addc_u32 s5, s25, 0
	v_writelane_b32 v254, s4, 6
	v_writelane_b32 v255, s81, 5
	v_writelane_b32 v255, s64, 6
	v_writelane_b32 v254, s5, 7
	s_add_u32 s4, s24, 0x1e00000
	s_addc_u32 s5, s25, 0
	v_writelane_b32 v254, s4, 8
	v_writelane_b32 v255, s65, 7
	v_writelane_b32 v255, s67, 8
	v_writelane_b32 v254, s5, 9
	s_add_u32 s4, s70, 0x1000
	s_addc_u32 s5, s71, 0
	v_writelane_b32 v254, s4, 10
	v_readlane_b32 s75, v252, 7
	v_readlane_b32 s76, v252, 8
	v_writelane_b32 v254, s5, 11
	s_add_u32 s4, s24, 0x1400000
	s_addc_u32 s5, s25, 0
	v_writelane_b32 v254, s4, 12
	s_cmp_lg_u64 s[70:71], 0
	v_readlane_b32 s77, v252, 9
	v_writelane_b32 v254, s5, 13
	s_cselect_b64 s[4:5], -1, 0
	v_writelane_b32 v254, s4, 14
	s_mov_b32 s86, 1
	s_movk_i32 s23, 0x2000
	v_writelane_b32 v254, s5, 15
	s_add_u32 s4, s48, 0x3000000
	s_addc_u32 s5, s49, 0
	v_writelane_b32 v254, s4, 16
	s_mov_b32 s19, 0x8000
	s_mov_b32 s22, 0x3e000000
	v_writelane_b32 v254, s5, 17
	s_add_u32 s4, s46, 0x3000000
	s_addc_u32 s5, s47, 0
	v_writelane_b32 v254, s4, 18
	s_mov_b32 s18, 0x3fb8aa3b
	s_nop 0
	v_writelane_b32 v254, s5, 19
	s_add_u32 s4, s82, 0x400000
	s_addc_u32 s5, s83, 0
;     __host__ __device__ bool next(int i, Unit& u) const {
;         const long L = (long)i * G + c; if (L >= nwg) return false;
;         int wgid = (int)L; { const int q = nwg / NXCD, r = nwg % NXCD, xcd = wgid % NXCD, off = wgid / NXCD; wgid = (xcd < r ? xcd * (q + 1) : r * (q + 1) + (xcd - r) * q) + off; }
;         const int nig = WGM * nN, gid = wgid / nig, fm = gid * WGM, gsz = (nM - fm) < WGM ? (nM - fm) : WGM;
;         u.pm = fm + ((wgid % nig) % gsz); u.pn = (wgid % nig) / gsz; return true;
	s_lshl_b32 s1, s31, 6
	v_writelane_b32 v254, s4, 20
	s_cmpk_lt_i32 s2, 0x800
	s_nop 0
	v_writelane_b32 v254, s5, 21
	s_cselect_b64 s[4:5], -1, 0
	v_writelane_b32 v254, s4, 22
	s_nop 1
	v_writelane_b32 v254, s5, 23
	s_lshl_b32 s4, s31, 8
	s_lshr_b32 s5, s31, 31
	v_writelane_b32 v254, s5, 24
	s_cmp_lt_i32 s31, 0
	s_mul_i32 s5, s31, 0x41
	s_cselect_b32 s1, s5, s1
	s_mul_i32 s5, s31, 0x101
	s_cselect_b32 s4, s5, s4
	s_add_i32 s1, s1, s30
	s_cmp_eq_u32 s28, 0x100
	s_cselect_b32 s5, 32, 0
	s_xor_b32 s1, s1, s5
	s_ashr_i32 s5, s1, 31
	s_lshr_b32 s5, s5, 27
	s_add_i32 s5, s1, s5
	s_and_b32 s8, s5, 0xffe0
	s_sub_i32 s1, s1, s8
	s_bfe_i32 s8, s1, 0x80000
	s_bfe_u32 s8, s8, 0x3000c
	s_add_i32 s8, s1, s8
	s_and_b32 s9, s8, 0xf8
	s_add_i32 s4, s4, s30
	s_sub_i32 s1, s1, s9
	s_ashr_i32 s9, s4, 31
	s_lshr_b32 s9, s9, 25
	s_add_i32 s9, s4, s9
	s_and_b32 s16, s9, 0xff80
	s_sub_i32 s4, s4, s16
	s_bfe_i32 s16, s4, 0x80000
	s_bfe_u32 s16, s16, 0x3000c
	s_add_i32 s16, s4, s16
	s_ashr_i32 s5, s5, 5
	s_and_b32 s17, s16, 0xf8
	s_lshl_b32 s5, s5, 3
	s_sext_i32_i8 s1, s1
	s_sub_i32 s4, s4, s17
	s_bfe_i32 s8, s8, 0x80000
	s_add_i32 s12, s5, s1
	s_ashr_i32 s1, s9, 7
	s_sext_i32_i16 s8, s8
	s_lshl_b32 s1, s1, 3
	s_bfe_i32 s5, s16, 0x80000
	s_sext_i32_i8 s4, s4
	v_writelane_b32 v254, s31, 25
	s_sext_i32_i16 s5, s5
	s_add_i32 s16, s1, s4
	s_lshr_b32 s4, s8, 3
	v_writelane_b32 v254, s30, 26
	s_ashr_i32 s1, s8, 3
	s_bfe_i64 s[8:9], s[4:5], 0x100000
	s_lshr_b32 s4, s5, 3
	v_writelane_b32 v254, s1, 27
	s_ashr_i32 s1, s5, 3
	s_bfe_i64 s[4:5], s[4:5], 0x100000
	v_writelane_b32 v254, s1, 28
	s_lshl_b64 s[4:5], s[4:5], 19
	v_writelane_b32 v254, s4, 29
	s_ashr_i32 s17, s16, 31
	s_ashr_i32 s13, s12, 31
	v_writelane_b32 v254, s5, 30
	s_mov_b32 s4, s16
	v_writelane_b32 v254, s4, 31
	s_movk_i32 s31, 0x4000
	s_mov_b32 s30, 0x3d800000
	v_writelane_b32 v254, s5, 32
	s_lshl_b64 s[4:5], s[16:17], 19
	s_add_u32 s4, s10, s4
	s_addc_u32 s5, s11, s5
	s_add_u32 s16, s4, 0x40000
	v_writelane_b32 v254, s4, 33
	s_addc_u32 s17, s5, 0
	s_nop 0
	v_writelane_b32 v254, s5, 34
	v_writelane_b32 v254, s16, 35
	s_nop 1
	v_writelane_b32 v254, s17, 36
	v_writelane_b32 v254, s12, 37
	s_lshl_b64 s[4:5], s[12:13], 21
	s_mov_b32 s17, 0
	v_writelane_b32 v254, s13, 38
	v_writelane_b32 v254, s8, 39
	s_mov_b32 s12, 0xc000
	s_mov_b32 s13, 0x3f317217
	v_writelane_b32 v254, s9, 40
	s_lshl_b64 s[8:9], s[8:9], 21
	v_writelane_b32 v254, s8, 41
	s_add_u32 s4, s14, s4
	s_addc_u32 s5, s15, s5
	v_writelane_b32 v254, s9, 42
	s_add_u32 s0, s4, 0x100000
	v_writelane_b32 v254, s4, 43
	s_addc_u32 s1, s5, 0
	s_lshl_b32 s66, s28, 6
	v_writelane_b32 v254, s5, 44
	v_writelane_b32 v254, s0, 45
	s_mov_b32 s8, 0
	s_mov_b64 s[4:5], 0x80
	v_writelane_b32 v254, s1, 46
	s_lshl_b32 s0, s28, 5
	s_addk_i32 s0, 0xf000
	v_writelane_b32 v254, s0, 47
	s_lshl_b32 s0, s28, 11
	s_add_i32 s0, s0, 0xfffc0000
	v_writelane_b32 v254, s0, 48
	s_lshl_b32 s0, s28, 7
	s_addk_i32 s0, 0xc000
	v_writelane_b32 v254, s0, 49
	s_lshl_b32 s0, s2, 6
	v_writelane_b32 v254, s0, 50
	s_lshl_b32 s0, s2, 5
	v_writelane_b32 v254, s0, 51
	s_mov_b32 s0, s88
	v_writelane_b32 v254, s0, 52
	v_writelane_b32 v255, s66, 9
	s_nop 0
	v_writelane_b32 v254, s1, 53
	s_add_i32 s0, s88, 0xd5c0
	v_writelane_b32 v254, s0, 54
	s_add_i32 s0, 0, 0x20000
	v_writelane_b32 v254, s0, 55
	s_add_i32 s0, 0, 0x23fc0
	v_writelane_b32 v254, s0, 56
	s_add_i32 s0, 0, 0x23fc4
	v_writelane_b32 v254, s0, 57
	s_add_i32 s0, 0, 0x1b800
	v_writelane_b32 v254, s0, 58
	s_add_i32 s0, 0, 0x1b200
	v_writelane_b32 v254, s0, 59
	v_writelane_b32 v254, s52, 60
	s_add_i32 s88, 0, 0x19800
	s_nop 0
	v_writelane_b32 v254, s53, 61
	v_cmp_gt_i64_e64 s[0:1], s[52:53], v[2:3]
	s_nop 1
	v_writelane_b32 v254, s0, 62
	s_nop 1
	v_writelane_b32 v254, s1, 63

;     __host__ __device__ bool next(int i, Unit& u) const {
;         const long L = (long)i * G + c; if (L >= nwg) return false;
;         int wgid = (int)L; { const int q = nwg / NXCD, r = nwg % NXCD, xcd = wgid % NXCD, off = wgid / NXCD; wgid = (xcd < r ? xcd * (q + 1) : r * (q + 1) + (xcd - r) * q) + off; }
;         const int nig = WGM * nN, gid = wgid / nig, fm = gid * WGM, gsz = (nM - fm) < WGM ? (nM - fm) : WGM;
;         u.pm = fm + ((wgid % nig) % gsz); u.pn = (wgid % nig) / gsz; return true;
.LBB0_1635:
	s_ashr_i32 s42, s51, 3
	s_add_i32 s42, s63, s42
	s_cmp_eq_u32 s28, 0x100
	s_cselect_b32 s43, 32, 0
	s_xor_b32 s42, s42, s43
	s_ashr_i32 s43, s42, 31
	s_lshr_b32 s43, s43, 27
	s_add_i32 s43, s42, s43
	s_ashr_i32 s51, s43, 5
	s_lshl_b32 s62, s51, 3
	s_sub_i32 s51, 0x80, s62
	s_min_i32 s63, s51, 8
	s_abs_i32 s51, s63
	v_cvt_f32_u32_e32 v0, s51
	s_sub_i32 s65, 0, s51
	s_andn2_b32 s43, s43, 31
	s_sub_i32 s42, s42, s43
	v_rcp_iflag_f32_e32 v0, v0
	s_abs_i32 s43, s42
	s_xor_b32 s64, s42, s63
	s_ashr_i32 s64, s64, 31
	v_mul_f32_e32 v0, 0x4f7ffffe, v0
	v_cvt_u32_f32_e32 v0, v0
	s_nop 0
	v_readfirstlane_b32 s76, v0
	s_mul_i32 s65, s65, s76
	s_mul_hi_u32 s65, s76, s65
	s_add_i32 s76, s76, s65
	s_mul_hi_u32 s65, s43, s76
	s_mul_i32 s76, s65, s51
	s_sub_i32 s43, s43, s76
	s_add_i32 s78, s65, 1
	s_sub_i32 s76, s43, s51
	s_cmp_ge_u32 s43, s51
	s_cselect_b32 s65, s78, s65
	s_cselect_b32 s43, s76, s43
	s_add_i32 s76, s65, 1
	s_cmp_ge_u32 s43, s51
	s_cselect_b32 s43, s76, s65
	s_xor_b32 s43, s43, s64
	s_sub_i32 s51, s43, s64
	s_mul_i32 s43, s51, s63
	s_sub_i32 s42, s42, s43
	s_add_i32 s76, s62, s42

;     __host__ __device__ bool next(int i, Unit& u) const {
;         const long L = (long)i * G + c; if (L >= nwg) return false;
;         int wgid = (int)L; { const int q = nwg / NXCD, r = nwg % NXCD, xcd = wgid % NXCD, off = wgid / NXCD; wgid = (xcd < r ? xcd * (q + 1) : r * (q + 1) + (xcd - r) * q) + off; }
;         const int nig = WGM * nN, gid = wgid / nig, fm = gid * WGM, gsz = (nM - fm) < WGM ? (nM - fm) : WGM;
;         u.pm = fm + ((wgid % nig) % gsz); u.pn = (wgid % nig) / gsz; return true;
.LBB0_1843:
	s_ashr_i32 s46, s48, 3
	s_add_i32 s46, s50, s46
	s_cmp_eq_u32 s28, 0x100
	s_cselect_b32 s47, 32, 0
	s_xor_b32 s46, s46, s47
	s_ashr_i32 s47, s46, 31
	s_lshr_b32 s47, s47, 27
	s_add_i32 s47, s46, s47
	s_ashr_i32 s48, s47, 5
	s_lshl_b32 s48, s48, 3
	s_sub_i32 s49, 0x80, s48
	s_min_i32 s49, s49, 8
	s_abs_i32 s50, s49
	v_cvt_f32_u32_e32 v0, s50
	s_sub_i32 s52, 0, s50
	s_andn2_b32 s47, s47, 31
	s_sub_i32 s47, s46, s47
	v_rcp_iflag_f32_e32 v0, v0
	s_abs_i32 s46, s47
	s_xor_b32 s51, s47, s49
	s_ashr_i32 s51, s51, 31
	v_mul_f32_e32 v0, 0x4f7ffffe, v0
	v_cvt_u32_f32_e32 v0, v0
	s_nop 0
	v_readfirstlane_b32 s53, v0
	s_mul_i32 s52, s52, s53
	s_mul_hi_u32 s52, s53, s52
	s_add_i32 s53, s53, s52
	s_mul_hi_u32 s52, s46, s53
	s_mul_i32 s53, s52, s50
	s_sub_i32 s46, s46, s53
	s_add_i32 s56, s52, 1
	s_sub_i32 s53, s46, s50
	s_cmp_ge_u32 s46, s50
	s_cselect_b32 s52, s56, s52
	s_cselect_b32 s46, s53, s46
	s_add_i32 s53, s52, 1
	s_cmp_ge_u32 s46, s50
	s_cselect_b32 s46, s53, s52
	s_xor_b32 s46, s46, s51
	s_sub_i32 s46, s46, s51
	s_mul_i32 s49, s46, s49
	s_sub_i32 s47, s47, s49
	s_add_i32 s48, s48, s47
